# projection epilogue q/k path: the four 8-byte stores of a row group issue after its last step so its rope loads do not wait on them
# speedup vs baseline: 1.1427x; 1.0021x over previous
.LBB0_961:
	s_or_b64 exec, exec, s[6:7]
	v_lshl_add_u64 v[158:159], s[0:1], 0, v[0:1]
	v_readlane_b32 s0, v254, 35
	v_readlane_b32 s1, v254, 36
	v_pk_mul_f32 v[172:173], v[154:155], v[132:133]
	v_lshlrev_b32_e32 v0, 1, v138
	v_mov_b64_e32 v[160:161], s[0:1]
	v_mad_i64_i32 v[160:161], s[0:1], v156, s52, v[160:161]
	s_lshl_b32 s0, s27, 1
	s_mov_b32 s1, s35
	v_lshl_add_u64 v[160:161], v[160:161], 0, s[0:1]
	v_lshl_add_u64 v[164:165], s[76:77], 1, v[160:161]
	v_mov_b32_e32 v160, v154
	v_mov_b32_e32 v161, v154
	v_pk_mul_f32 v[162:163], v[160:161], v[162:163]
	v_lshl_add_u64 v[132:133], v[164:165], 0, v[0:1]
	v_cvt_pk_bf16_f32 v240, v172, v173
	v_cvt_pk_bf16_f32 v241, v162, v163
	global_load_dwordx4 v[162:165], v[158:159], off offset:64
	v_mov_b32_e32 v131, v130
	v_pk_mul_f32 v[172:173], v[122:123], v[130:131]
	s_waitcnt vmcnt(0)
	v_mov_b64_e32 v[228:229], v[162:163]
	v_mov_b64_e32 v[230:231], v[164:165]
	v_pk_mul_f32 v[162:163], v[172:173], v[162:163]
	v_pk_mul_f32 v[172:173], v[124:125], v[130:131]
	s_nop 0
	v_pk_mul_f32 v[164:165], v[172:173], v[164:165]
	s_and_saveexec_b64 s[0:1], vcc
	s_cbranch_execz .LBB0_963
	v_readlane_b32 s6, v254, 6
	v_readlane_b32 s7, v254, 7
	s_nop 4
	global_load_dwordx4 v[172:175], v157, s[6:7] offset:64
	s_waitcnt vmcnt(0)
	v_pk_mul_f32 v[178:179], v[162:163], v[172:173] op_sel:[1,1] op_sel_hi:[1,0]
	v_mul_f32_e32 v0, v165, v175
	v_pk_mul_f32 v[176:177], v[162:163], v[172:173]
	v_pk_fma_f32 v[162:163], v[162:163], v[172:173], v[178:179] op_sel_hi:[0,1,1]
	v_pk_fma_f32 v[172:173], v[164:165], v[174:175], v[0:1] op_sel_hi:[1,1,0] neg_lo:[0,0,1] neg_hi:[0,0,1]
	v_mul_f32_e32 v0, v165, v174
	v_pk_fma_f32 v[174:175], v[164:165], v[174:175], v[0:1] op_sel:[0,1,0] op_sel_hi:[1,0,0]
	v_sub_f32_e32 v162, v176, v178
	v_mov_b32_e32 v164, v172
	v_mov_b32_e32 v165, v174
.LBB0_963:
	s_or_b64 exec, exec, s[0:1]
	v_pk_mul_f32 v[160:161], v[160:161], v[164:165]
	v_pk_mul_f32 v[162:163], v[154:155], v[162:163]
	v_pk_mul_f32 v[164:165], v[118:119], v[130:131]
	v_cvt_pk_bf16_f32 v242, v162, v163
	v_cvt_pk_bf16_f32 v243, v160, v161
	global_load_dwordx4 v[160:163], v[158:159], off offset:128
	s_waitcnt vmcnt(0)
	v_mov_b64_e32 v[232:233], v[160:161]
	v_mov_b64_e32 v[234:235], v[162:163]
	v_pk_mul_f32 v[160:161], v[164:165], v[160:161]
	v_pk_mul_f32 v[164:165], v[120:121], v[130:131]
	s_nop 0
	v_pk_mul_f32 v[164:165], v[164:165], v[162:163]
	s_and_saveexec_b64 s[0:1], vcc
	s_cbranch_execz .LBB0_965
	global_load_dwordx4 v[172:175], v[140:141], off
	s_waitcnt vmcnt(0)
	v_pk_mul_f32 v[176:177], v[160:161], v[172:173] op_sel:[1,1] op_sel_hi:[1,0]
	v_mul_f32_e32 v0, v165, v175
	v_pk_mul_f32 v[162:163], v[160:161], v[172:173]
	v_pk_fma_f32 v[160:161], v[160:161], v[172:173], v[176:177] op_sel_hi:[0,1,1]
	v_pk_fma_f32 v[172:173], v[164:165], v[174:175], v[0:1] op_sel_hi:[1,1,0] neg_lo:[0,0,1] neg_hi:[0,0,1]
	v_mul_f32_e32 v0, v165, v174
	v_pk_fma_f32 v[174:175], v[164:165], v[174:175], v[0:1] op_sel:[0,1,0] op_sel_hi:[1,0,0]
	v_sub_f32_e32 v160, v162, v176
	v_mov_b32_e32 v164, v172
	v_mov_b32_e32 v165, v174
.LBB0_965:
	s_or_b64 exec, exec, s[0:1]
	v_mov_b32_e32 v162, v154
	v_mov_b32_e32 v163, v154
	v_pk_mul_f32 v[164:165], v[162:163], v[164:165]
	v_pk_mul_f32 v[160:161], v[154:155], v[160:161]
	v_pk_mul_f32 v[172:173], v[116:117], v[130:131]
	v_cvt_pk_bf16_f32 v244, v160, v161
	v_cvt_pk_bf16_f32 v245, v164, v165
	global_load_dwordx4 v[158:161], v[158:159], off offset:192
	v_pk_mul_f32 v[164:165], v[114:115], v[130:131]
	s_waitcnt vmcnt(0)
	v_mov_b64_e32 v[236:237], v[158:159]
	v_mov_b64_e32 v[238:239], v[160:161]
	v_pk_mul_f32 v[130:131], v[164:165], v[158:159]
	v_pk_mul_f32 v[158:159], v[172:173], v[160:161]
	s_and_saveexec_b64 s[0:1], vcc
	s_cbranch_execz .LBB0_967
	global_load_dwordx4 v[172:175], v[140:141], off offset:64
	s_waitcnt vmcnt(0)
	v_pk_mul_f32 v[164:165], v[130:131], v[172:173] op_sel:[1,1] op_sel_hi:[1,0]
	v_mul_f32_e32 v0, v159, v175
	v_pk_mul_f32 v[160:161], v[130:131], v[172:173]
	v_pk_fma_f32 v[130:131], v[130:131], v[172:173], v[164:165] op_sel_hi:[0,1,1]
	v_pk_fma_f32 v[172:173], v[158:159], v[174:175], v[0:1] op_sel_hi:[1,1,0] neg_lo:[0,0,1] neg_hi:[0,0,1]
	v_mul_f32_e32 v0, v159, v174
	v_pk_fma_f32 v[174:175], v[158:159], v[174:175], v[0:1] op_sel:[0,1,0] op_sel_hi:[1,0,0]
	v_sub_f32_e32 v130, v160, v164
	v_mov_b32_e32 v158, v172
	v_mov_b32_e32 v159, v174
.LBB0_967:
	s_or_b64 exec, exec, s[0:1]
	v_pk_mul_f32 v[158:159], v[162:163], v[158:159]
	v_pk_mul_f32 v[130:131], v[154:155], v[130:131]
	s_mov_b64 s[0:1], 0
	v_cvt_pk_bf16_f32 v246, v130, v131
	v_cvt_pk_bf16_f32 v247, v158, v159
	global_store_dwordx2 v[132:133], v[240:241], off
	global_store_dwordx2 v[132:133], v[242:243], off offset:32
	global_store_dwordx2 v[132:133], v[244:245], off offset:64
	global_store_dwordx2 v[132:133], v[246:247], off offset:96

.LBB0_1009:
	s_or_b64 exec, exec, s[4:5]
	v_lshl_add_u64 v[120:121], s[0:1], 0, v[0:1]
	v_readlane_b32 s0, v254, 35
	v_readlane_b32 s1, v254, 36
	v_pk_mul_f32 v[128:129], v[154:155], v[116:117]
	v_lshlrev_b32_e32 v0, 1, v138
	v_mov_b64_e32 v[122:123], s[0:1]
	v_mad_i64_i32 v[122:123], s[0:1], v118, s52, v[122:123]
	s_lshl_b32 s0, s27, 1
	s_mov_b32 s1, s35
	v_lshl_add_u64 v[122:123], v[122:123], 0, s[0:1]
	v_lshl_add_u64 v[126:127], s[76:77], 1, v[122:123]
	v_mov_b32_e32 v122, v154
	v_mov_b32_e32 v123, v154
	v_pk_mul_f32 v[124:125], v[122:123], v[124:125]
	v_lshl_add_u64 v[116:117], v[126:127], 0, v[0:1]
	v_cvt_pk_bf16_f32 v240, v128, v129
	v_cvt_pk_bf16_f32 v241, v124, v125
	s_nop 1
	v_mov_b64_e32 v[124:125], v[228:229]
	v_mov_b64_e32 v[126:127], v[230:231]
	v_mov_b32_e32 v115, v114
	v_pk_mul_f32 v[128:129], v[106:107], v[114:115]
	v_pk_mul_f32 v[124:125], v[128:129], v[124:125]
	v_pk_mul_f32 v[128:129], v[108:109], v[114:115]
	s_nop 0
	v_pk_mul_f32 v[126:127], v[128:129], v[126:127]
	s_and_saveexec_b64 s[0:1], vcc
	s_cbranch_execz .LBB0_1011
	v_readlane_b32 s4, v254, 6
	v_readlane_b32 s5, v254, 7
	s_nop 4
	global_load_dwordx4 v[128:131], v119, s[4:5] offset:64
	s_waitcnt vmcnt(0)
	v_pk_mul_f32 v[156:157], v[124:125], v[128:129] op_sel:[1,1] op_sel_hi:[1,0]
	v_mul_f32_e32 v0, v127, v131
	v_pk_mul_f32 v[132:133], v[124:125], v[128:129]
	v_pk_fma_f32 v[124:125], v[124:125], v[128:129], v[156:157] op_sel_hi:[0,1,1]
	v_pk_fma_f32 v[128:129], v[126:127], v[130:131], v[0:1] op_sel_hi:[1,1,0] neg_lo:[0,0,1] neg_hi:[0,0,1]
	v_mul_f32_e32 v0, v127, v130
	v_pk_fma_f32 v[130:131], v[126:127], v[130:131], v[0:1] op_sel:[0,1,0] op_sel_hi:[1,0,0]
	v_sub_f32_e32 v124, v132, v156
	v_mov_b32_e32 v126, v128
	v_mov_b32_e32 v127, v130
.LBB0_1011:
	s_or_b64 exec, exec, s[0:1]
	v_pk_mul_f32 v[122:123], v[122:123], v[126:127]
	v_pk_mul_f32 v[124:125], v[154:155], v[124:125]
	v_pk_mul_f32 v[126:127], v[102:103], v[114:115]
	v_cvt_pk_bf16_f32 v242, v124, v125
	v_cvt_pk_bf16_f32 v243, v122, v123
	s_nop 1
	v_mov_b64_e32 v[122:123], v[232:233]
	v_mov_b64_e32 v[124:125], v[234:235]
	v_pk_mul_f32 v[122:123], v[126:127], v[122:123]
	v_pk_mul_f32 v[126:127], v[104:105], v[114:115]
	s_nop 0
	v_pk_mul_f32 v[126:127], v[126:127], v[124:125]
	s_and_saveexec_b64 s[0:1], vcc
	s_cbranch_execz .LBB0_1013
	global_load_dwordx4 v[128:131], v[142:143], off
	s_waitcnt vmcnt(0)
	v_pk_mul_f32 v[132:133], v[122:123], v[128:129] op_sel:[1,1] op_sel_hi:[1,0]
	v_mul_f32_e32 v0, v127, v131
	v_pk_mul_f32 v[124:125], v[122:123], v[128:129]
	v_pk_fma_f32 v[122:123], v[122:123], v[128:129], v[132:133] op_sel_hi:[0,1,1]
	v_pk_fma_f32 v[128:129], v[126:127], v[130:131], v[0:1] op_sel_hi:[1,1,0] neg_lo:[0,0,1] neg_hi:[0,0,1]
	v_mul_f32_e32 v0, v127, v130
	v_pk_fma_f32 v[130:131], v[126:127], v[130:131], v[0:1] op_sel:[0,1,0] op_sel_hi:[1,0,0]
	v_sub_f32_e32 v122, v124, v132
	v_mov_b32_e32 v126, v128
	v_mov_b32_e32 v127, v130
.LBB0_1013:
	s_or_b64 exec, exec, s[0:1]
	v_mov_b32_e32 v124, v154
	v_mov_b32_e32 v125, v154
	v_pk_mul_f32 v[126:127], v[124:125], v[126:127]
	v_pk_mul_f32 v[122:123], v[154:155], v[122:123]
	v_pk_mul_f32 v[128:129], v[100:101], v[114:115]
	v_cvt_pk_bf16_f32 v244, v122, v123
	v_cvt_pk_bf16_f32 v245, v126, v127
	s_nop 1
	v_mov_b64_e32 v[120:121], v[236:237]
	v_mov_b64_e32 v[122:123], v[238:239]
	v_pk_mul_f32 v[126:127], v[98:99], v[114:115]
	v_pk_mul_f32 v[114:115], v[126:127], v[120:121]
	v_pk_mul_f32 v[120:121], v[128:129], v[122:123]
	s_and_saveexec_b64 s[0:1], vcc
	s_cbranch_execz .LBB0_1015
	global_load_dwordx4 v[126:129], v[142:143], off offset:64
	s_waitcnt vmcnt(0)
	v_pk_mul_f32 v[130:131], v[114:115], v[126:127] op_sel:[1,1] op_sel_hi:[1,0]
	v_mul_f32_e32 v0, v121, v129
	v_pk_mul_f32 v[122:123], v[114:115], v[126:127]
	v_pk_fma_f32 v[114:115], v[114:115], v[126:127], v[130:131] op_sel_hi:[0,1,1]
	v_pk_fma_f32 v[126:127], v[120:121], v[128:129], v[0:1] op_sel_hi:[1,1,0] neg_lo:[0,0,1] neg_hi:[0,0,1]
	v_mul_f32_e32 v0, v121, v128
	v_pk_fma_f32 v[128:129], v[120:121], v[128:129], v[0:1] op_sel:[0,1,0] op_sel_hi:[1,0,0]
	v_sub_f32_e32 v114, v122, v130
	v_mov_b32_e32 v120, v126
	v_mov_b32_e32 v121, v128
.LBB0_1015:
	s_or_b64 exec, exec, s[0:1]
	v_pk_mul_f32 v[120:121], v[124:125], v[120:121]
	v_pk_mul_f32 v[114:115], v[154:155], v[114:115]
	s_nop 0
	v_cvt_pk_bf16_f32 v246, v114, v115
	v_cvt_pk_bf16_f32 v247, v120, v121
	global_store_dwordx2 v[116:117], v[240:241], off
	global_store_dwordx2 v[116:117], v[242:243], off offset:32
	global_store_dwordx2 v[116:117], v[244:245], off offset:64
	global_store_dwordx2 v[116:117], v[246:247], off offset:96

.LBB0_1057:
	s_or_b64 exec, exec, s[4:5]
	v_lshl_add_u64 v[104:105], s[0:1], 0, v[0:1]
	v_readlane_b32 s0, v254, 35
	v_readlane_b32 s1, v254, 36
	v_pk_mul_f32 v[112:113], v[154:155], v[100:101]
	v_lshlrev_b32_e32 v0, 1, v138
	v_mov_b64_e32 v[106:107], s[0:1]
	v_mad_i64_i32 v[106:107], s[0:1], v102, s52, v[106:107]
	s_lshl_b32 s0, s27, 1
	s_mov_b32 s1, s35
	v_lshl_add_u64 v[106:107], v[106:107], 0, s[0:1]
	v_lshl_add_u64 v[110:111], s[76:77], 1, v[106:107]
	v_mov_b32_e32 v106, v154
	v_mov_b32_e32 v107, v154
	v_pk_mul_f32 v[108:109], v[106:107], v[108:109]
	v_lshl_add_u64 v[100:101], v[110:111], 0, v[0:1]
	v_cvt_pk_bf16_f32 v240, v112, v113
	v_cvt_pk_bf16_f32 v241, v108, v109
	s_nop 1
	v_mov_b64_e32 v[108:109], v[228:229]
	v_mov_b64_e32 v[110:111], v[230:231]
	v_mov_b32_e32 v99, v98
	v_pk_mul_f32 v[112:113], v[90:91], v[98:99]
	v_pk_mul_f32 v[108:109], v[112:113], v[108:109]
	v_pk_mul_f32 v[112:113], v[92:93], v[98:99]
	s_nop 0
	v_pk_mul_f32 v[110:111], v[112:113], v[110:111]
	s_and_saveexec_b64 s[0:1], vcc
	s_cbranch_execz .LBB0_1059
	v_readlane_b32 s4, v254, 6
	v_readlane_b32 s5, v254, 7
	s_nop 4
	global_load_dwordx4 v[112:115], v103, s[4:5] offset:64
	s_waitcnt vmcnt(0)
	v_pk_mul_f32 v[118:119], v[108:109], v[112:113] op_sel:[1,1] op_sel_hi:[1,0]
	v_mul_f32_e32 v0, v111, v115
	v_pk_mul_f32 v[116:117], v[108:109], v[112:113]
	v_pk_fma_f32 v[108:109], v[108:109], v[112:113], v[118:119] op_sel_hi:[0,1,1]
	v_pk_fma_f32 v[112:113], v[110:111], v[114:115], v[0:1] op_sel_hi:[1,1,0] neg_lo:[0,0,1] neg_hi:[0,0,1]
	v_mul_f32_e32 v0, v111, v114
	v_pk_fma_f32 v[114:115], v[110:111], v[114:115], v[0:1] op_sel:[0,1,0] op_sel_hi:[1,0,0]
	v_sub_f32_e32 v108, v116, v118
	v_mov_b32_e32 v110, v112
	v_mov_b32_e32 v111, v114
.LBB0_1059:
	s_or_b64 exec, exec, s[0:1]
	v_pk_mul_f32 v[106:107], v[106:107], v[110:111]
	v_pk_mul_f32 v[108:109], v[154:155], v[108:109]
	v_pk_mul_f32 v[110:111], v[86:87], v[98:99]
	v_cvt_pk_bf16_f32 v242, v108, v109
	v_cvt_pk_bf16_f32 v243, v106, v107
	s_nop 1
	v_mov_b64_e32 v[106:107], v[232:233]
	v_mov_b64_e32 v[108:109], v[234:235]
	v_pk_mul_f32 v[106:107], v[110:111], v[106:107]
	v_pk_mul_f32 v[110:111], v[88:89], v[98:99]
	s_nop 0
	v_pk_mul_f32 v[110:111], v[110:111], v[108:109]
	s_and_saveexec_b64 s[0:1], vcc
	s_cbranch_execz .LBB0_1061
	global_load_dwordx4 v[112:115], v[144:145], off
	s_waitcnt vmcnt(0)
	v_pk_mul_f32 v[116:117], v[106:107], v[112:113] op_sel:[1,1] op_sel_hi:[1,0]
	v_mul_f32_e32 v0, v111, v115
	v_pk_mul_f32 v[108:109], v[106:107], v[112:113]
	v_pk_fma_f32 v[106:107], v[106:107], v[112:113], v[116:117] op_sel_hi:[0,1,1]
	v_pk_fma_f32 v[112:113], v[110:111], v[114:115], v[0:1] op_sel_hi:[1,1,0] neg_lo:[0,0,1] neg_hi:[0,0,1]
	v_mul_f32_e32 v0, v111, v114
	v_pk_fma_f32 v[114:115], v[110:111], v[114:115], v[0:1] op_sel:[0,1,0] op_sel_hi:[1,0,0]
	v_sub_f32_e32 v106, v108, v116
	v_mov_b32_e32 v110, v112
	v_mov_b32_e32 v111, v114
.LBB0_1061:
	s_or_b64 exec, exec, s[0:1]
	v_mov_b32_e32 v108, v154
	v_mov_b32_e32 v109, v154
	v_pk_mul_f32 v[110:111], v[108:109], v[110:111]
	v_pk_mul_f32 v[106:107], v[154:155], v[106:107]
	v_pk_mul_f32 v[112:113], v[84:85], v[98:99]
	v_cvt_pk_bf16_f32 v244, v106, v107
	v_cvt_pk_bf16_f32 v245, v110, v111
	s_nop 1
	v_mov_b64_e32 v[104:105], v[236:237]
	v_mov_b64_e32 v[106:107], v[238:239]
	v_pk_mul_f32 v[110:111], v[82:83], v[98:99]
	v_pk_mul_f32 v[98:99], v[110:111], v[104:105]
	v_pk_mul_f32 v[104:105], v[112:113], v[106:107]
	s_and_saveexec_b64 s[0:1], vcc
	s_cbranch_execz .LBB0_1063
	global_load_dwordx4 v[110:113], v[144:145], off offset:64
	s_waitcnt vmcnt(0)
	v_pk_mul_f32 v[114:115], v[98:99], v[110:111] op_sel:[1,1] op_sel_hi:[1,0]
	v_mul_f32_e32 v0, v105, v113
	v_pk_mul_f32 v[106:107], v[98:99], v[110:111]
	v_pk_fma_f32 v[98:99], v[98:99], v[110:111], v[114:115] op_sel_hi:[0,1,1]
	v_pk_fma_f32 v[110:111], v[104:105], v[112:113], v[0:1] op_sel_hi:[1,1,0] neg_lo:[0,0,1] neg_hi:[0,0,1]
	v_mul_f32_e32 v0, v105, v112
	v_pk_fma_f32 v[112:113], v[104:105], v[112:113], v[0:1] op_sel:[0,1,0] op_sel_hi:[1,0,0]
	v_sub_f32_e32 v98, v106, v114
	v_mov_b32_e32 v104, v110
	v_mov_b32_e32 v105, v112
.LBB0_1063:
	s_or_b64 exec, exec, s[0:1]
	v_pk_mul_f32 v[104:105], v[108:109], v[104:105]
	v_pk_mul_f32 v[98:99], v[154:155], v[98:99]
	s_nop 0
	v_cvt_pk_bf16_f32 v246, v98, v99
	v_cvt_pk_bf16_f32 v247, v104, v105
	global_store_dwordx2 v[100:101], v[240:241], off
	global_store_dwordx2 v[100:101], v[242:243], off offset:32
	global_store_dwordx2 v[100:101], v[244:245], off offset:64
	global_store_dwordx2 v[100:101], v[246:247], off offset:96

.LBB0_1105:
	s_or_b64 exec, exec, s[4:5]
	v_lshl_add_u64 v[88:89], s[0:1], 0, v[0:1]
	v_readlane_b32 s0, v254, 35
	v_readlane_b32 s1, v254, 36
	v_pk_mul_f32 v[96:97], v[154:155], v[84:85]
	v_lshlrev_b32_e32 v0, 1, v138
	v_mov_b64_e32 v[90:91], s[0:1]
	v_mad_i64_i32 v[90:91], s[0:1], v86, s52, v[90:91]
	s_lshl_b32 s0, s27, 1
	s_mov_b32 s1, s35
	v_lshl_add_u64 v[90:91], v[90:91], 0, s[0:1]
	v_lshl_add_u64 v[94:95], s[76:77], 1, v[90:91]
	v_mov_b32_e32 v90, v154
	v_mov_b32_e32 v91, v154
	v_pk_mul_f32 v[92:93], v[90:91], v[92:93]
	v_lshl_add_u64 v[84:85], v[94:95], 0, v[0:1]
	v_cvt_pk_bf16_f32 v240, v96, v97
	v_cvt_pk_bf16_f32 v241, v92, v93
	s_nop 1
	v_mov_b64_e32 v[92:93], v[228:229]
	v_mov_b64_e32 v[94:95], v[230:231]
	v_mov_b32_e32 v83, v82
	v_pk_mul_f32 v[96:97], v[74:75], v[82:83]
	v_pk_mul_f32 v[92:93], v[96:97], v[92:93]
	v_pk_mul_f32 v[96:97], v[76:77], v[82:83]
	s_nop 0
	v_pk_mul_f32 v[94:95], v[96:97], v[94:95]
	s_and_saveexec_b64 s[0:1], vcc
	s_cbranch_execz .LBB0_1107
	v_readlane_b32 s4, v254, 6
	v_readlane_b32 s5, v254, 7
	s_nop 4
	global_load_dwordx4 v[96:99], v87, s[4:5] offset:64
	s_waitcnt vmcnt(0)
	v_pk_mul_f32 v[102:103], v[92:93], v[96:97] op_sel:[1,1] op_sel_hi:[1,0]
	v_mul_f32_e32 v0, v95, v99
	v_pk_mul_f32 v[100:101], v[92:93], v[96:97]
	v_pk_fma_f32 v[92:93], v[92:93], v[96:97], v[102:103] op_sel_hi:[0,1,1]
	v_pk_fma_f32 v[96:97], v[94:95], v[98:99], v[0:1] op_sel_hi:[1,1,0] neg_lo:[0,0,1] neg_hi:[0,0,1]
	v_mul_f32_e32 v0, v95, v98
	v_pk_fma_f32 v[98:99], v[94:95], v[98:99], v[0:1] op_sel:[0,1,0] op_sel_hi:[1,0,0]
	v_sub_f32_e32 v92, v100, v102
	v_mov_b32_e32 v94, v96
	v_mov_b32_e32 v95, v98
.LBB0_1107:
	s_or_b64 exec, exec, s[0:1]
	v_pk_mul_f32 v[90:91], v[90:91], v[94:95]
	v_pk_mul_f32 v[92:93], v[154:155], v[92:93]
	v_pk_mul_f32 v[94:95], v[70:71], v[82:83]
	v_cvt_pk_bf16_f32 v242, v92, v93
	v_cvt_pk_bf16_f32 v243, v90, v91
	s_nop 1
	v_mov_b64_e32 v[90:91], v[232:233]
	v_mov_b64_e32 v[92:93], v[234:235]
	v_pk_mul_f32 v[90:91], v[94:95], v[90:91]
	v_pk_mul_f32 v[94:95], v[72:73], v[82:83]
	s_nop 0
	v_pk_mul_f32 v[94:95], v[94:95], v[92:93]
	s_and_saveexec_b64 s[0:1], vcc
	s_cbranch_execz .LBB0_1109
	global_load_dwordx4 v[96:99], v[146:147], off
	s_waitcnt vmcnt(0)
	v_pk_mul_f32 v[100:101], v[90:91], v[96:97] op_sel:[1,1] op_sel_hi:[1,0]
	v_mul_f32_e32 v0, v95, v99
	v_pk_mul_f32 v[92:93], v[90:91], v[96:97]
	v_pk_fma_f32 v[90:91], v[90:91], v[96:97], v[100:101] op_sel_hi:[0,1,1]
	v_pk_fma_f32 v[96:97], v[94:95], v[98:99], v[0:1] op_sel_hi:[1,1,0] neg_lo:[0,0,1] neg_hi:[0,0,1]
	v_mul_f32_e32 v0, v95, v98
	v_pk_fma_f32 v[98:99], v[94:95], v[98:99], v[0:1] op_sel:[0,1,0] op_sel_hi:[1,0,0]
	v_sub_f32_e32 v90, v92, v100
	v_mov_b32_e32 v94, v96
	v_mov_b32_e32 v95, v98
.LBB0_1109:
	s_or_b64 exec, exec, s[0:1]
	v_mov_b32_e32 v92, v154
	v_mov_b32_e32 v93, v154
	v_pk_mul_f32 v[94:95], v[92:93], v[94:95]
	v_pk_mul_f32 v[90:91], v[154:155], v[90:91]
	v_pk_mul_f32 v[96:97], v[68:69], v[82:83]
	v_cvt_pk_bf16_f32 v244, v90, v91
	v_cvt_pk_bf16_f32 v245, v94, v95
	s_nop 1
	v_mov_b64_e32 v[88:89], v[236:237]
	v_mov_b64_e32 v[90:91], v[238:239]
	v_pk_mul_f32 v[94:95], v[66:67], v[82:83]
	v_pk_mul_f32 v[82:83], v[94:95], v[88:89]
	v_pk_mul_f32 v[88:89], v[96:97], v[90:91]
	s_and_saveexec_b64 s[0:1], vcc
	s_cbranch_execz .LBB0_1111
	global_load_dwordx4 v[94:97], v[146:147], off offset:64
	s_waitcnt vmcnt(0)
	v_pk_mul_f32 v[98:99], v[82:83], v[94:95] op_sel:[1,1] op_sel_hi:[1,0]
	v_mul_f32_e32 v0, v89, v97
	v_pk_mul_f32 v[90:91], v[82:83], v[94:95]
	v_pk_fma_f32 v[82:83], v[82:83], v[94:95], v[98:99] op_sel_hi:[0,1,1]
	v_pk_fma_f32 v[94:95], v[88:89], v[96:97], v[0:1] op_sel_hi:[1,1,0] neg_lo:[0,0,1] neg_hi:[0,0,1]
	v_mul_f32_e32 v0, v89, v96
	v_pk_fma_f32 v[96:97], v[88:89], v[96:97], v[0:1] op_sel:[0,1,0] op_sel_hi:[1,0,0]
	v_sub_f32_e32 v82, v90, v98
	v_mov_b32_e32 v88, v94
	v_mov_b32_e32 v89, v96
.LBB0_1111:
	s_or_b64 exec, exec, s[0:1]
	v_pk_mul_f32 v[88:89], v[92:93], v[88:89]
	v_pk_mul_f32 v[82:83], v[154:155], v[82:83]
	s_nop 0
	v_cvt_pk_bf16_f32 v246, v82, v83
	v_cvt_pk_bf16_f32 v247, v88, v89
	global_store_dwordx2 v[84:85], v[240:241], off
	global_store_dwordx2 v[84:85], v[242:243], off offset:32
	global_store_dwordx2 v[84:85], v[244:245], off offset:64
	global_store_dwordx2 v[84:85], v[246:247], off offset:96

.LBB0_1153:
	s_or_b64 exec, exec, s[4:5]
	v_lshl_add_u64 v[72:73], s[0:1], 0, v[0:1]
	v_readlane_b32 s0, v254, 35
	v_readlane_b32 s1, v254, 36
	v_pk_mul_f32 v[80:81], v[154:155], v[68:69]
	v_lshlrev_b32_e32 v0, 1, v138
	v_mov_b64_e32 v[74:75], s[0:1]
	v_mad_i64_i32 v[74:75], s[0:1], v70, s52, v[74:75]
	s_lshl_b32 s0, s27, 1
	s_mov_b32 s1, s35
	v_lshl_add_u64 v[74:75], v[74:75], 0, s[0:1]
	v_lshl_add_u64 v[78:79], s[76:77], 1, v[74:75]
	v_mov_b32_e32 v74, v154
	v_mov_b32_e32 v75, v154
	v_pk_mul_f32 v[76:77], v[74:75], v[76:77]
	v_lshl_add_u64 v[68:69], v[78:79], 0, v[0:1]
	v_cvt_pk_bf16_f32 v240, v80, v81
	v_cvt_pk_bf16_f32 v241, v76, v77
	s_nop 1
	v_mov_b64_e32 v[76:77], v[228:229]
	v_mov_b64_e32 v[78:79], v[230:231]
	v_mov_b32_e32 v67, v66
	v_pk_mul_f32 v[80:81], v[58:59], v[66:67]
	v_pk_mul_f32 v[76:77], v[80:81], v[76:77]
	v_pk_mul_f32 v[80:81], v[60:61], v[66:67]
	s_nop 0
	v_pk_mul_f32 v[78:79], v[80:81], v[78:79]
	s_and_saveexec_b64 s[0:1], vcc
	s_cbranch_execz .LBB0_1155
	v_readlane_b32 s4, v254, 6
	v_readlane_b32 s5, v254, 7
	s_nop 4
	global_load_dwordx4 v[80:83], v71, s[4:5] offset:64
	s_waitcnt vmcnt(0)
	v_pk_mul_f32 v[86:87], v[76:77], v[80:81] op_sel:[1,1] op_sel_hi:[1,0]
	v_mul_f32_e32 v0, v79, v83
	v_pk_mul_f32 v[84:85], v[76:77], v[80:81]
	v_pk_fma_f32 v[76:77], v[76:77], v[80:81], v[86:87] op_sel_hi:[0,1,1]
	v_pk_fma_f32 v[80:81], v[78:79], v[82:83], v[0:1] op_sel_hi:[1,1,0] neg_lo:[0,0,1] neg_hi:[0,0,1]
	v_mul_f32_e32 v0, v79, v82
	v_pk_fma_f32 v[82:83], v[78:79], v[82:83], v[0:1] op_sel:[0,1,0] op_sel_hi:[1,0,0]
	v_sub_f32_e32 v76, v84, v86
	v_mov_b32_e32 v78, v80
	v_mov_b32_e32 v79, v82
.LBB0_1155:
	s_or_b64 exec, exec, s[0:1]
	v_pk_mul_f32 v[74:75], v[74:75], v[78:79]
	v_pk_mul_f32 v[76:77], v[154:155], v[76:77]
	v_pk_mul_f32 v[78:79], v[54:55], v[66:67]
	v_cvt_pk_bf16_f32 v242, v76, v77
	v_cvt_pk_bf16_f32 v243, v74, v75
	s_nop 1
	v_mov_b64_e32 v[74:75], v[232:233]
	v_mov_b64_e32 v[76:77], v[234:235]
	v_pk_mul_f32 v[74:75], v[78:79], v[74:75]
	v_pk_mul_f32 v[78:79], v[56:57], v[66:67]
	s_nop 0
	v_pk_mul_f32 v[78:79], v[78:79], v[76:77]
	s_and_saveexec_b64 s[0:1], vcc
	s_cbranch_execz .LBB0_1157
	global_load_dwordx4 v[80:83], v[140:141], off
	s_waitcnt vmcnt(0)
	v_pk_mul_f32 v[84:85], v[74:75], v[80:81] op_sel:[1,1] op_sel_hi:[1,0]
	v_mul_f32_e32 v0, v79, v83
	v_pk_mul_f32 v[76:77], v[74:75], v[80:81]
	v_pk_fma_f32 v[74:75], v[74:75], v[80:81], v[84:85] op_sel_hi:[0,1,1]
	v_pk_fma_f32 v[80:81], v[78:79], v[82:83], v[0:1] op_sel_hi:[1,1,0] neg_lo:[0,0,1] neg_hi:[0,0,1]
	v_mul_f32_e32 v0, v79, v82
	v_pk_fma_f32 v[82:83], v[78:79], v[82:83], v[0:1] op_sel:[0,1,0] op_sel_hi:[1,0,0]
	v_sub_f32_e32 v74, v76, v84
	v_mov_b32_e32 v78, v80
	v_mov_b32_e32 v79, v82
.LBB0_1157:
	s_or_b64 exec, exec, s[0:1]
	v_mov_b32_e32 v76, v154
	v_mov_b32_e32 v77, v154
	v_pk_mul_f32 v[78:79], v[76:77], v[78:79]
	v_pk_mul_f32 v[74:75], v[154:155], v[74:75]
	v_pk_mul_f32 v[80:81], v[52:53], v[66:67]
	v_cvt_pk_bf16_f32 v244, v74, v75
	v_cvt_pk_bf16_f32 v245, v78, v79
	s_nop 1
	v_mov_b64_e32 v[72:73], v[236:237]
	v_mov_b64_e32 v[74:75], v[238:239]
	v_pk_mul_f32 v[78:79], v[50:51], v[66:67]
	v_pk_mul_f32 v[66:67], v[78:79], v[72:73]
	v_pk_mul_f32 v[72:73], v[80:81], v[74:75]
	s_and_saveexec_b64 s[0:1], vcc
	s_cbranch_execz .LBB0_1159
	global_load_dwordx4 v[78:81], v[140:141], off offset:64
	s_waitcnt vmcnt(0)
	v_pk_mul_f32 v[82:83], v[66:67], v[78:79] op_sel:[1,1] op_sel_hi:[1,0]
	v_mul_f32_e32 v0, v73, v81
	v_pk_mul_f32 v[74:75], v[66:67], v[78:79]
	v_pk_fma_f32 v[66:67], v[66:67], v[78:79], v[82:83] op_sel_hi:[0,1,1]
	v_pk_fma_f32 v[78:79], v[72:73], v[80:81], v[0:1] op_sel_hi:[1,1,0] neg_lo:[0,0,1] neg_hi:[0,0,1]
	v_mul_f32_e32 v0, v73, v80
	v_pk_fma_f32 v[80:81], v[72:73], v[80:81], v[0:1] op_sel:[0,1,0] op_sel_hi:[1,0,0]
	v_sub_f32_e32 v66, v74, v82
	v_mov_b32_e32 v72, v78
	v_mov_b32_e32 v73, v80
.LBB0_1159:
	s_or_b64 exec, exec, s[0:1]
	v_pk_mul_f32 v[72:73], v[76:77], v[72:73]
	v_pk_mul_f32 v[66:67], v[154:155], v[66:67]
	s_nop 0
	v_cvt_pk_bf16_f32 v246, v66, v67
	v_cvt_pk_bf16_f32 v247, v72, v73
	global_store_dwordx2 v[68:69], v[240:241], off
	global_store_dwordx2 v[68:69], v[242:243], off offset:32
	global_store_dwordx2 v[68:69], v[244:245], off offset:64
	global_store_dwordx2 v[68:69], v[246:247], off offset:96

.LBB0_1201:
	s_or_b64 exec, exec, s[4:5]
	v_lshl_add_u64 v[56:57], s[0:1], 0, v[0:1]
	v_readlane_b32 s0, v254, 35
	v_readlane_b32 s1, v254, 36
	v_pk_mul_f32 v[64:65], v[154:155], v[52:53]
	v_lshlrev_b32_e32 v0, 1, v138
	v_mov_b64_e32 v[58:59], s[0:1]
	v_mad_i64_i32 v[58:59], s[0:1], v54, s52, v[58:59]
	s_lshl_b32 s0, s27, 1
	s_mov_b32 s1, s35
	v_lshl_add_u64 v[58:59], v[58:59], 0, s[0:1]
	v_lshl_add_u64 v[62:63], s[76:77], 1, v[58:59]
	v_mov_b32_e32 v58, v154
	v_mov_b32_e32 v59, v154
	v_pk_mul_f32 v[60:61], v[58:59], v[60:61]
	v_lshl_add_u64 v[52:53], v[62:63], 0, v[0:1]
	v_cvt_pk_bf16_f32 v240, v64, v65
	v_cvt_pk_bf16_f32 v241, v60, v61
	s_nop 1
	v_mov_b64_e32 v[60:61], v[228:229]
	v_mov_b64_e32 v[62:63], v[230:231]
	v_mov_b32_e32 v51, v50
	v_pk_mul_f32 v[64:65], v[42:43], v[50:51]
	v_pk_mul_f32 v[60:61], v[64:65], v[60:61]
	v_pk_mul_f32 v[64:65], v[44:45], v[50:51]
	s_nop 0
	v_pk_mul_f32 v[62:63], v[64:65], v[62:63]
	s_and_saveexec_b64 s[0:1], vcc
	s_cbranch_execz .LBB0_1203
	v_readlane_b32 s4, v254, 6
	v_readlane_b32 s5, v254, 7
	s_nop 4
	global_load_dwordx4 v[64:67], v55, s[4:5] offset:64
	s_waitcnt vmcnt(0)
	v_pk_mul_f32 v[70:71], v[60:61], v[64:65] op_sel:[1,1] op_sel_hi:[1,0]
	v_mul_f32_e32 v0, v63, v67
	v_pk_mul_f32 v[68:69], v[60:61], v[64:65]
	v_pk_fma_f32 v[60:61], v[60:61], v[64:65], v[70:71] op_sel_hi:[0,1,1]
	v_pk_fma_f32 v[64:65], v[62:63], v[66:67], v[0:1] op_sel_hi:[1,1,0] neg_lo:[0,0,1] neg_hi:[0,0,1]
	v_mul_f32_e32 v0, v63, v66
	v_pk_fma_f32 v[66:67], v[62:63], v[66:67], v[0:1] op_sel:[0,1,0] op_sel_hi:[1,0,0]
	v_sub_f32_e32 v60, v68, v70
	v_mov_b32_e32 v62, v64
	v_mov_b32_e32 v63, v66
.LBB0_1203:
	s_or_b64 exec, exec, s[0:1]
	v_pk_mul_f32 v[58:59], v[58:59], v[62:63]
	v_pk_mul_f32 v[60:61], v[154:155], v[60:61]
	v_pk_mul_f32 v[62:63], v[38:39], v[50:51]
	v_cvt_pk_bf16_f32 v242, v60, v61
	v_cvt_pk_bf16_f32 v243, v58, v59
	s_nop 1
	v_mov_b64_e32 v[58:59], v[232:233]
	v_mov_b64_e32 v[60:61], v[234:235]
	v_pk_mul_f32 v[58:59], v[62:63], v[58:59]
	v_pk_mul_f32 v[62:63], v[40:41], v[50:51]
	s_nop 0
	v_pk_mul_f32 v[62:63], v[62:63], v[60:61]
	s_and_saveexec_b64 s[0:1], vcc
	s_cbranch_execz .LBB0_1205
	global_load_dwordx4 v[64:67], v[142:143], off
	s_waitcnt vmcnt(0)
	v_pk_mul_f32 v[68:69], v[58:59], v[64:65] op_sel:[1,1] op_sel_hi:[1,0]
	v_mul_f32_e32 v0, v63, v67
	v_pk_mul_f32 v[60:61], v[58:59], v[64:65]
	v_pk_fma_f32 v[58:59], v[58:59], v[64:65], v[68:69] op_sel_hi:[0,1,1]
	v_pk_fma_f32 v[64:65], v[62:63], v[66:67], v[0:1] op_sel_hi:[1,1,0] neg_lo:[0,0,1] neg_hi:[0,0,1]
	v_mul_f32_e32 v0, v63, v66
	v_pk_fma_f32 v[66:67], v[62:63], v[66:67], v[0:1] op_sel:[0,1,0] op_sel_hi:[1,0,0]
	v_sub_f32_e32 v58, v60, v68
	v_mov_b32_e32 v62, v64
	v_mov_b32_e32 v63, v66
.LBB0_1205:
	s_or_b64 exec, exec, s[0:1]
	v_mov_b32_e32 v60, v154
	v_mov_b32_e32 v61, v154
	v_pk_mul_f32 v[62:63], v[60:61], v[62:63]
	v_pk_mul_f32 v[58:59], v[154:155], v[58:59]
	v_pk_mul_f32 v[64:65], v[36:37], v[50:51]
	v_cvt_pk_bf16_f32 v244, v58, v59
	v_cvt_pk_bf16_f32 v245, v62, v63
	s_nop 1
	v_mov_b64_e32 v[56:57], v[236:237]
	v_mov_b64_e32 v[58:59], v[238:239]
	v_pk_mul_f32 v[62:63], v[34:35], v[50:51]
	v_pk_mul_f32 v[50:51], v[62:63], v[56:57]
	v_pk_mul_f32 v[56:57], v[64:65], v[58:59]
	s_and_saveexec_b64 s[0:1], vcc
	s_cbranch_execz .LBB0_1207
	global_load_dwordx4 v[62:65], v[142:143], off offset:64
	s_waitcnt vmcnt(0)
	v_pk_mul_f32 v[66:67], v[50:51], v[62:63] op_sel:[1,1] op_sel_hi:[1,0]
	v_mul_f32_e32 v0, v57, v65
	v_pk_mul_f32 v[58:59], v[50:51], v[62:63]
	v_pk_fma_f32 v[50:51], v[50:51], v[62:63], v[66:67] op_sel_hi:[0,1,1]
	v_pk_fma_f32 v[62:63], v[56:57], v[64:65], v[0:1] op_sel_hi:[1,1,0] neg_lo:[0,0,1] neg_hi:[0,0,1]
	v_mul_f32_e32 v0, v57, v64
	v_pk_fma_f32 v[64:65], v[56:57], v[64:65], v[0:1] op_sel:[0,1,0] op_sel_hi:[1,0,0]
	v_sub_f32_e32 v50, v58, v66
	v_mov_b32_e32 v56, v62
	v_mov_b32_e32 v57, v64
.LBB0_1207:
	s_or_b64 exec, exec, s[0:1]
	v_pk_mul_f32 v[56:57], v[60:61], v[56:57]
	v_pk_mul_f32 v[50:51], v[154:155], v[50:51]
	s_nop 0
	v_cvt_pk_bf16_f32 v246, v50, v51
	v_cvt_pk_bf16_f32 v247, v56, v57
	global_store_dwordx2 v[52:53], v[240:241], off
	global_store_dwordx2 v[52:53], v[242:243], off offset:32
	global_store_dwordx2 v[52:53], v[244:245], off offset:64
	global_store_dwordx2 v[52:53], v[246:247], off offset:96

.LBB0_1249:
	s_or_b64 exec, exec, s[4:5]
	v_lshl_add_u64 v[40:41], s[0:1], 0, v[0:1]
	v_readlane_b32 s0, v254, 35
	v_readlane_b32 s1, v254, 36
	v_pk_mul_f32 v[48:49], v[154:155], v[36:37]
	v_lshlrev_b32_e32 v0, 1, v138
	v_mov_b64_e32 v[42:43], s[0:1]
	v_mad_i64_i32 v[42:43], s[0:1], v38, s52, v[42:43]
	s_lshl_b32 s0, s27, 1
	s_mov_b32 s1, s35
	v_lshl_add_u64 v[42:43], v[42:43], 0, s[0:1]
	v_lshl_add_u64 v[46:47], s[76:77], 1, v[42:43]
	v_mov_b32_e32 v42, v154
	v_mov_b32_e32 v43, v154
	v_pk_mul_f32 v[44:45], v[42:43], v[44:45]
	v_lshl_add_u64 v[36:37], v[46:47], 0, v[0:1]
	v_cvt_pk_bf16_f32 v240, v48, v49
	v_cvt_pk_bf16_f32 v241, v44, v45
	s_nop 1
	v_mov_b64_e32 v[44:45], v[228:229]
	v_mov_b64_e32 v[46:47], v[230:231]
	v_mov_b32_e32 v35, v34
	v_pk_mul_f32 v[48:49], v[26:27], v[34:35]
	v_pk_mul_f32 v[44:45], v[48:49], v[44:45]
	v_pk_mul_f32 v[48:49], v[28:29], v[34:35]
	s_nop 0
	v_pk_mul_f32 v[46:47], v[48:49], v[46:47]
	s_and_saveexec_b64 s[0:1], vcc
	s_cbranch_execz .LBB0_1251
	v_readlane_b32 s4, v254, 6
	v_readlane_b32 s5, v254, 7
	s_nop 4
	global_load_dwordx4 v[48:51], v39, s[4:5] offset:64
	s_waitcnt vmcnt(0)
	v_pk_mul_f32 v[54:55], v[44:45], v[48:49] op_sel:[1,1] op_sel_hi:[1,0]
	v_mul_f32_e32 v0, v47, v51
	v_pk_mul_f32 v[52:53], v[44:45], v[48:49]
	v_pk_fma_f32 v[44:45], v[44:45], v[48:49], v[54:55] op_sel_hi:[0,1,1]
	v_pk_fma_f32 v[48:49], v[46:47], v[50:51], v[0:1] op_sel_hi:[1,1,0] neg_lo:[0,0,1] neg_hi:[0,0,1]
	v_mul_f32_e32 v0, v47, v50
	v_pk_fma_f32 v[50:51], v[46:47], v[50:51], v[0:1] op_sel:[0,1,0] op_sel_hi:[1,0,0]
	v_sub_f32_e32 v44, v52, v54
	v_mov_b32_e32 v46, v48
	v_mov_b32_e32 v47, v50
.LBB0_1251:
	s_or_b64 exec, exec, s[0:1]
	v_pk_mul_f32 v[42:43], v[42:43], v[46:47]
	v_pk_mul_f32 v[44:45], v[154:155], v[44:45]
	v_pk_mul_f32 v[46:47], v[22:23], v[34:35]
	v_cvt_pk_bf16_f32 v242, v44, v45
	v_cvt_pk_bf16_f32 v243, v42, v43
	s_nop 1
	v_mov_b64_e32 v[42:43], v[232:233]
	v_mov_b64_e32 v[44:45], v[234:235]
	v_pk_mul_f32 v[42:43], v[46:47], v[42:43]
	v_pk_mul_f32 v[46:47], v[24:25], v[34:35]
	s_nop 0
	v_pk_mul_f32 v[46:47], v[46:47], v[44:45]
	s_and_saveexec_b64 s[0:1], vcc
	s_cbranch_execz .LBB0_1253
	global_load_dwordx4 v[48:51], v[144:145], off
	s_waitcnt vmcnt(0)
	v_pk_mul_f32 v[52:53], v[42:43], v[48:49] op_sel:[1,1] op_sel_hi:[1,0]
	v_mul_f32_e32 v0, v47, v51
	v_pk_mul_f32 v[44:45], v[42:43], v[48:49]
	v_pk_fma_f32 v[42:43], v[42:43], v[48:49], v[52:53] op_sel_hi:[0,1,1]
	v_pk_fma_f32 v[48:49], v[46:47], v[50:51], v[0:1] op_sel_hi:[1,1,0] neg_lo:[0,0,1] neg_hi:[0,0,1]
	v_mul_f32_e32 v0, v47, v50
	v_pk_fma_f32 v[50:51], v[46:47], v[50:51], v[0:1] op_sel:[0,1,0] op_sel_hi:[1,0,0]
	v_sub_f32_e32 v42, v44, v52
	v_mov_b32_e32 v46, v48
	v_mov_b32_e32 v47, v50
.LBB0_1253:
	s_or_b64 exec, exec, s[0:1]
	v_mov_b32_e32 v44, v154
	v_mov_b32_e32 v45, v154
	v_pk_mul_f32 v[46:47], v[44:45], v[46:47]
	v_pk_mul_f32 v[42:43], v[154:155], v[42:43]
	v_pk_mul_f32 v[48:49], v[20:21], v[34:35]
	v_cvt_pk_bf16_f32 v244, v42, v43
	v_cvt_pk_bf16_f32 v245, v46, v47
	s_nop 1
	v_mov_b64_e32 v[40:41], v[236:237]
	v_mov_b64_e32 v[42:43], v[238:239]
	v_pk_mul_f32 v[46:47], v[18:19], v[34:35]
	v_pk_mul_f32 v[34:35], v[46:47], v[40:41]
	v_pk_mul_f32 v[40:41], v[48:49], v[42:43]
	s_and_saveexec_b64 s[0:1], vcc
	s_cbranch_execz .LBB0_1255
	global_load_dwordx4 v[46:49], v[144:145], off offset:64
	s_waitcnt vmcnt(0)
	v_pk_mul_f32 v[50:51], v[34:35], v[46:47] op_sel:[1,1] op_sel_hi:[1,0]
	v_mul_f32_e32 v0, v41, v49
	v_pk_mul_f32 v[42:43], v[34:35], v[46:47]
	v_pk_fma_f32 v[34:35], v[34:35], v[46:47], v[50:51] op_sel_hi:[0,1,1]
	v_pk_fma_f32 v[46:47], v[40:41], v[48:49], v[0:1] op_sel_hi:[1,1,0] neg_lo:[0,0,1] neg_hi:[0,0,1]
	v_mul_f32_e32 v0, v41, v48
	v_pk_fma_f32 v[48:49], v[40:41], v[48:49], v[0:1] op_sel:[0,1,0] op_sel_hi:[1,0,0]
	v_sub_f32_e32 v34, v42, v50
	v_mov_b32_e32 v40, v46
	v_mov_b32_e32 v41, v48
.LBB0_1255:
	s_or_b64 exec, exec, s[0:1]
	v_pk_mul_f32 v[40:41], v[44:45], v[40:41]
	v_pk_mul_f32 v[34:35], v[154:155], v[34:35]
	s_nop 0
	v_cvt_pk_bf16_f32 v246, v34, v35
	v_cvt_pk_bf16_f32 v247, v40, v41
	global_store_dwordx2 v[36:37], v[240:241], off
	global_store_dwordx2 v[36:37], v[242:243], off offset:32
	global_store_dwordx2 v[36:37], v[244:245], off offset:64
	global_store_dwordx2 v[36:37], v[246:247], off offset:96

.LBB0_1297:
	s_or_b64 exec, exec, s[2:3]
	v_lshl_add_u64 v[24:25], s[0:1], 0, v[0:1]
	v_readlane_b32 s0, v254, 35
	v_readlane_b32 s1, v254, 36
	s_lshl_b32 s34, s27, 1
	v_pk_mul_f32 v[32:33], v[154:155], v[20:21]
	v_mov_b64_e32 v[26:27], s[0:1]
	v_mad_i64_i32 v[26:27], s[0:1], v22, s52, v[26:27]
	v_lshl_add_u64 v[26:27], v[26:27], 0, s[34:35]
	v_lshl_add_u64 v[30:31], s[76:77], 1, v[26:27]
	v_mov_b32_e32 v26, v154
	v_mov_b32_e32 v27, v154
	v_pk_mul_f32 v[28:29], v[26:27], v[28:29]
	v_lshlrev_b32_e32 v0, 1, v138
	v_lshl_add_u64 v[20:21], v[30:31], 0, v[0:1]
	v_cvt_pk_bf16_f32 v240, v32, v33
	v_cvt_pk_bf16_f32 v241, v28, v29
	s_nop 1
	v_mov_b64_e32 v[28:29], v[228:229]
	v_mov_b64_e32 v[30:31], v[230:231]
	v_mov_b32_e32 v19, v18
	v_pk_mul_f32 v[32:33], v[10:11], v[18:19]
	v_pk_mul_f32 v[28:29], v[32:33], v[28:29]
	v_pk_mul_f32 v[32:33], v[12:13], v[18:19]
	s_nop 0
	v_pk_mul_f32 v[30:31], v[32:33], v[30:31]
	s_and_saveexec_b64 s[0:1], vcc
	s_cbranch_execz .LBB0_1299
	v_readlane_b32 s2, v254, 6
	v_readlane_b32 s3, v254, 7
	s_nop 4
	global_load_dwordx4 v[32:35], v23, s[2:3] offset:64
	s_waitcnt vmcnt(0)
	v_pk_mul_f32 v[38:39], v[28:29], v[32:33] op_sel:[1,1] op_sel_hi:[1,0]
	v_mul_f32_e32 v0, v31, v35
	v_pk_mul_f32 v[36:37], v[28:29], v[32:33]
	v_pk_fma_f32 v[28:29], v[28:29], v[32:33], v[38:39] op_sel_hi:[0,1,1]
	v_pk_fma_f32 v[32:33], v[30:31], v[34:35], v[0:1] op_sel_hi:[1,1,0] neg_lo:[0,0,1] neg_hi:[0,0,1]
	v_mul_f32_e32 v0, v31, v34
	v_pk_fma_f32 v[34:35], v[30:31], v[34:35], v[0:1] op_sel:[0,1,0] op_sel_hi:[1,0,0]
	v_sub_f32_e32 v28, v36, v38
	v_mov_b32_e32 v30, v32
	v_mov_b32_e32 v31, v34
.LBB0_1299:
	s_or_b64 exec, exec, s[0:1]
	v_pk_mul_f32 v[26:27], v[26:27], v[30:31]
	v_pk_mul_f32 v[28:29], v[154:155], v[28:29]
	v_pk_mul_f32 v[30:31], v[6:7], v[18:19]
	v_cvt_pk_bf16_f32 v242, v28, v29
	v_cvt_pk_bf16_f32 v243, v26, v27
	s_nop 1
	v_mov_b64_e32 v[26:27], v[232:233]
	v_mov_b64_e32 v[28:29], v[234:235]
	v_pk_mul_f32 v[26:27], v[30:31], v[26:27]
	v_pk_mul_f32 v[30:31], v[8:9], v[18:19]
	s_nop 0
	v_pk_mul_f32 v[30:31], v[30:31], v[28:29]
	s_and_saveexec_b64 s[0:1], vcc
	s_cbranch_execz .LBB0_1301
	global_load_dwordx4 v[32:35], v[146:147], off
	s_waitcnt vmcnt(0)
	v_pk_mul_f32 v[36:37], v[26:27], v[32:33] op_sel:[1,1] op_sel_hi:[1,0]
	v_mul_f32_e32 v0, v31, v35
	v_pk_mul_f32 v[28:29], v[26:27], v[32:33]
	v_pk_fma_f32 v[26:27], v[26:27], v[32:33], v[36:37] op_sel_hi:[0,1,1]
	v_pk_fma_f32 v[32:33], v[30:31], v[34:35], v[0:1] op_sel_hi:[1,1,0] neg_lo:[0,0,1] neg_hi:[0,0,1]
	v_mul_f32_e32 v0, v31, v34
	v_pk_fma_f32 v[34:35], v[30:31], v[34:35], v[0:1] op_sel:[0,1,0] op_sel_hi:[1,0,0]
	v_sub_f32_e32 v26, v28, v36
	v_mov_b32_e32 v30, v32
	v_mov_b32_e32 v31, v34
.LBB0_1301:
	s_or_b64 exec, exec, s[0:1]
	v_mov_b32_e32 v28, v154
	v_mov_b32_e32 v29, v154
	v_pk_mul_f32 v[30:31], v[28:29], v[30:31]
	v_pk_mul_f32 v[26:27], v[154:155], v[26:27]
	v_pk_mul_f32 v[32:33], v[4:5], v[18:19]
	v_cvt_pk_bf16_f32 v244, v26, v27
	v_cvt_pk_bf16_f32 v245, v30, v31
	s_nop 1
	v_mov_b64_e32 v[24:25], v[236:237]
	v_mov_b64_e32 v[26:27], v[238:239]
	v_pk_mul_f32 v[30:31], v[2:3], v[18:19]
	v_pk_mul_f32 v[18:19], v[30:31], v[24:25]
	v_pk_mul_f32 v[24:25], v[32:33], v[26:27]
	s_and_saveexec_b64 s[0:1], vcc
	s_cbranch_execz .LBB0_1303
	global_load_dwordx4 v[30:33], v[146:147], off offset:64
	s_waitcnt vmcnt(0)
	v_pk_mul_f32 v[34:35], v[18:19], v[30:31] op_sel:[1,1] op_sel_hi:[1,0]
	v_mul_f32_e32 v0, v25, v33
	v_pk_mul_f32 v[26:27], v[18:19], v[30:31]
	v_pk_fma_f32 v[18:19], v[18:19], v[30:31], v[34:35] op_sel_hi:[0,1,1]
	v_pk_fma_f32 v[30:31], v[24:25], v[32:33], v[0:1] op_sel_hi:[1,1,0] neg_lo:[0,0,1] neg_hi:[0,0,1]
	v_mul_f32_e32 v0, v25, v32
	v_pk_fma_f32 v[32:33], v[24:25], v[32:33], v[0:1] op_sel:[0,1,0] op_sel_hi:[1,0,0]
	v_sub_f32_e32 v18, v26, v34
	v_mov_b32_e32 v24, v30
	v_mov_b32_e32 v25, v32
.LBB0_1303:
	s_or_b64 exec, exec, s[0:1]
	v_pk_mul_f32 v[24:25], v[28:29], v[24:25]
	v_pk_mul_f32 v[18:19], v[154:155], v[18:19]
	s_nop 0
	v_cvt_pk_bf16_f32 v246, v18, v19
	v_cvt_pk_bf16_f32 v247, v24, v25
	global_store_dwordx2 v[20:21], v[240:241], off
	global_store_dwordx2 v[20:21], v[242:243], off offset:32
	global_store_dwordx2 v[20:21], v[244:245], off offset:64
	global_store_dwordx2 v[20:21], v[246:247], off offset:96
